# grid barrier arrival path: workgroup count taken from a register instead of a dependent load of the barrier struct; barrier-pointer s_load overlapped with the L2 write-back
# speedup vs baseline: 1.0646x; 1.0533x over previous
; __global__ void __launch_bounds__(256, 2) mega(P p, int ph_lo, int ph_hi) {
;     ...
;       grid.sync();
.LBB0_1058:
	v_readlane_b32 s2, v252, 0
	v_readlane_b32 s3, v252, 1
	v_readlane_b32 s8, v253, 5
	s_nop 4
	s_load_dwordx2 s[2:3], s[2:3], 0x58
	buffer_wbl2 sc1
	s_waitcnt vmcnt(0)
	s_mov_b64 s[4:5], exec
	v_mbcnt_lo_u32_b32 v1, s4, 0
	v_mbcnt_hi_u32_b32 v1, s5, v1
	v_cmp_eq_u32_e32 vcc, 0, v1
	s_waitcnt lgkmcnt(0)
	v_mov_b32_e32 v0, s8
	s_and_saveexec_b64 s[6:7], vcc
	s_cbranch_execz .LBB0_1060
	s_bcnt1_i32_b64 s4, s[4:5]
	v_mov_b32_e32 v2, s4
	global_atomic_add v2, v177, v2, s[2:3] offset:32 sc0
